# prep: remaining transposes (w_o, branch, q/kv up-proj) issue all 16 tile loads before one wait; adaLN matvec keeps 32 weight loads in flight per iteration
# speedup vs baseline: 1.1434x; 1.0033x over previous
; #define LAUNDER_IDS const int tid__ = launder_v((int)threadIdx.x); const int blk__ = launder_s((int)blockIdx.x); (void)tid__; (void)blk__;
; DI void do_transpose(const float* __restrict__ src, int K, int N, u16* __restrict__ dst, const float* __restrict__ ksc, int perm, int tile, float* tl) {
;   LAUNDER_IDS
;   const int ntn = (N + 63) >> 6;
;   const int kt = tile / ntn, nt = tile - kt * ntn;
;   const int k0 = kt * 64, n0 = nt * 64;
;   const int tid = tid__;
;   __syncthreads();
; #pragma unroll 4
;   for (int i = 0; i < 16; ++i) {
;     const int kk = i * 4 + (tid >> 6), nn = tid & 63;
;     float v = 0.f;
;     if (n0 + nn < N) v = src[(size_t)(k0 + kk) * N + n0 + nn];
;     if (ksc) v *= ksc[k0 + kk];
;     tl[kk * 65 + nn] = v;
;   }
;   __syncthreads();
.LBB0_134:
	s_andn2_b64 vcc, exec, s[4:5]
	s_cbranch_vccnz .LBB0_155
	s_add_i32 s7, s97, 0xfffff9a8
	s_lshl_b64 s[4:5], s[54:55], 22
	s_waitcnt lgkmcnt(0)
	s_add_u32 s48, s20, s4
	v_mov_b32_e32 v1, v163
	s_mov_b32 s4, s2
	s_addc_u32 s58, s21, s5
	s_lshr_b32 s6, s7, 4
	s_lshl_b32 s4, s6, 10
	s_lshl_b32 s5, s7, 6
	s_sub_i32 s4, s5, s4
	v_and_b32_e32 v6, 63, v1
	s_ashr_i32 s5, s4, 31
	v_ashrrev_i32_e32 v7, 6, v1
	v_or_b32_e32 v1, s4, v6
	s_lshl_b64 s[4:5], s[4:5], 2
	s_add_u32 s4, s48, s4
	s_addc_u32 s5, s58, s5
	v_lshlrev_b32_e32 v2, 2, v6
	v_lshl_add_u64 v[4:5], s[4:5], 0, v[2:3]
	v_mad_u64_u32 v[8:9], s[4:5], v7, s82, v[2:3]
	s_mul_i32 s4, s54, 0xf70
	s_sub_i32 s4, s73, s4
	s_lshr_b32 s7, s4, 4
	v_cmp_gt_i32_e32 vcc, s83, v1
	v_lshl_add_u32 v1, s7, 6, v7
	s_mov_b32 s48, 0
	s_barrier
	s_branch .LBB0_137
.LBB0_137:
	v_mov_b32_e32 v16, 0
	v_mov_b32_e32 v17, 0
	v_mov_b32_e32 v18, 0
	v_mov_b32_e32 v19, 0
	v_mov_b32_e32 v20, 0
	v_mov_b32_e32 v21, 0
	v_mov_b32_e32 v22, 0
	v_mov_b32_e32 v23, 0
	v_mov_b32_e32 v24, 0
	v_mov_b32_e32 v25, 0
	v_mov_b32_e32 v26, 0
	v_mov_b32_e32 v27, 0
	v_mov_b32_e32 v28, 0
	v_mov_b32_e32 v29, 0
	v_mov_b32_e32 v30, 0
	v_mov_b32_e32 v31, 0
	s_and_saveexec_b64 s[4:5], vcc
	s_cbranch_execz .Lprep_wo_done
	v_mov_b32_e32 v10, v1
	v_ashrrev_i32_e32 v11, 31, v10
	v_lshlrev_b64 v[10:11], 12, v[10:11]
	v_lshl_add_u64 v[10:11], v[4:5], 0, v[10:11]
	global_load_dword v16, v[10:11], off
	v_add_u32_e32 v10, 4, v1
	v_ashrrev_i32_e32 v11, 31, v10
	v_lshlrev_b64 v[10:11], 12, v[10:11]
	v_lshl_add_u64 v[10:11], v[4:5], 0, v[10:11]
	global_load_dword v17, v[10:11], off
	v_add_u32_e32 v10, 8, v1
	v_ashrrev_i32_e32 v11, 31, v10
	v_lshlrev_b64 v[10:11], 12, v[10:11]
	v_lshl_add_u64 v[10:11], v[4:5], 0, v[10:11]
	global_load_dword v18, v[10:11], off
	v_add_u32_e32 v10, 12, v1
	v_ashrrev_i32_e32 v11, 31, v10
	v_lshlrev_b64 v[10:11], 12, v[10:11]
	v_lshl_add_u64 v[10:11], v[4:5], 0, v[10:11]
	global_load_dword v19, v[10:11], off
	v_add_u32_e32 v10, 16, v1
	v_ashrrev_i32_e32 v11, 31, v10
	v_lshlrev_b64 v[10:11], 12, v[10:11]
	v_lshl_add_u64 v[10:11], v[4:5], 0, v[10:11]
	global_load_dword v20, v[10:11], off
	v_add_u32_e32 v10, 20, v1
	v_ashrrev_i32_e32 v11, 31, v10
	v_lshlrev_b64 v[10:11], 12, v[10:11]
	v_lshl_add_u64 v[10:11], v[4:5], 0, v[10:11]
	global_load_dword v21, v[10:11], off
	v_add_u32_e32 v10, 24, v1
	v_ashrrev_i32_e32 v11, 31, v10
	v_lshlrev_b64 v[10:11], 12, v[10:11]
	v_lshl_add_u64 v[10:11], v[4:5], 0, v[10:11]
	global_load_dword v22, v[10:11], off
	v_add_u32_e32 v10, 28, v1
	v_ashrrev_i32_e32 v11, 31, v10
	v_lshlrev_b64 v[10:11], 12, v[10:11]
	v_lshl_add_u64 v[10:11], v[4:5], 0, v[10:11]
	global_load_dword v23, v[10:11], off
	v_add_u32_e32 v10, 32, v1
	v_ashrrev_i32_e32 v11, 31, v10
	v_lshlrev_b64 v[10:11], 12, v[10:11]
	v_lshl_add_u64 v[10:11], v[4:5], 0, v[10:11]
	global_load_dword v24, v[10:11], off
	v_add_u32_e32 v10, 36, v1
	v_ashrrev_i32_e32 v11, 31, v10
	v_lshlrev_b64 v[10:11], 12, v[10:11]
	v_lshl_add_u64 v[10:11], v[4:5], 0, v[10:11]
	global_load_dword v25, v[10:11], off
	v_add_u32_e32 v10, 40, v1
	v_ashrrev_i32_e32 v11, 31, v10
	v_lshlrev_b64 v[10:11], 12, v[10:11]
	v_lshl_add_u64 v[10:11], v[4:5], 0, v[10:11]
	global_load_dword v26, v[10:11], off
	v_add_u32_e32 v10, 44, v1
	v_ashrrev_i32_e32 v11, 31, v10
	v_lshlrev_b64 v[10:11], 12, v[10:11]
	v_lshl_add_u64 v[10:11], v[4:5], 0, v[10:11]
	global_load_dword v27, v[10:11], off
	v_add_u32_e32 v10, 48, v1
	v_ashrrev_i32_e32 v11, 31, v10
	v_lshlrev_b64 v[10:11], 12, v[10:11]
	v_lshl_add_u64 v[10:11], v[4:5], 0, v[10:11]
	global_load_dword v28, v[10:11], off
	v_add_u32_e32 v10, 52, v1
	v_ashrrev_i32_e32 v11, 31, v10
	v_lshlrev_b64 v[10:11], 12, v[10:11]
	v_lshl_add_u64 v[10:11], v[4:5], 0, v[10:11]
	global_load_dword v29, v[10:11], off
	v_add_u32_e32 v10, 56, v1
	v_ashrrev_i32_e32 v11, 31, v10
	v_lshlrev_b64 v[10:11], 12, v[10:11]
	v_lshl_add_u64 v[10:11], v[4:5], 0, v[10:11]
	global_load_dword v30, v[10:11], off
	v_add_u32_e32 v10, 60, v1
	v_ashrrev_i32_e32 v11, 31, v10
	v_lshlrev_b64 v[10:11], 12, v[10:11]
	v_lshl_add_u64 v[10:11], v[4:5], 0, v[10:11]
	global_load_dword v31, v[10:11], off
.Lprep_wo_done:
	s_or_b64 exec, exec, s[4:5]
	s_waitcnt vmcnt(0)
	ds_write_b32 v8, v16
	ds_write_b32 v8, v17 offset:1040
	ds_write_b32 v8, v18 offset:2080
	ds_write_b32 v8, v19 offset:3120
	ds_write_b32 v8, v20 offset:4160
	ds_write_b32 v8, v21 offset:5200
	ds_write_b32 v8, v22 offset:6240
	ds_write_b32 v8, v23 offset:7280
	ds_write_b32 v8, v24 offset:8320
	ds_write_b32 v8, v25 offset:9360
	ds_write_b32 v8, v26 offset:10400
	ds_write_b32 v8, v27 offset:11440
	ds_write_b32 v8, v28 offset:12480
	ds_write_b32 v8, v29 offset:13520
	ds_write_b32 v8, v30 offset:14560
	ds_write_b32 v8, v31 offset:15600
.LBB0_145:
	s_lshl_b32 s4, s6, 7
	s_add_u32 s4, s56, s4
	s_addc_u32 s5, s57, 0
	v_lshlrev_b32_e32 v2, 1, v6
	v_lshl_add_u64 v[4:5], s[4:5], 0, v[2:3]
	s_mov_b64 s[4:5], 0xd20000
	v_lshl_add_u64 v[4:5], v[4:5], 0, s[4:5]
	v_add_u32_e32 v1, s66, v7
	s_lshl_b32 s4, s7, 10
	v_subrev_u32_e32 v1, s4, v1
	s_mul_i32 s4, s54, 0x3dc00
	v_lshlrev_b32_e32 v2, 2, v7
	v_subrev_u32_e32 v1, s4, v1
	v_mad_u32_u24 v2, v6, s82, v2
	s_mov_b32 s6, 0
	s_waitcnt lgkmcnt(0)
	s_barrier
	s_branch .LBB0_147

; #define LAUNDER_IDS const int tid__ = launder_v((int)threadIdx.x); const int blk__ = launder_s((int)blockIdx.x); (void)tid__; (void)blk__;
; DI void do_transpose(const float* __restrict__ src, int K, int N, u16* __restrict__ dst, const float* __restrict__ ksc, int perm, int tile, float* tl) {
;   LAUNDER_IDS
;   const int ntn = (N + 63) >> 6;
;   const int kt = tile / ntn, nt = tile - kt * ntn;
;   const int k0 = kt * 64, n0 = nt * 64;
;   const int tid = tid__;
;   __syncthreads();
; #pragma unroll 4
;   for (int i = 0; i < 16; ++i) {
;     const int kk = i * 4 + (tid >> 6), nn = tid & 63;
;     float v = 0.f;
;     if (n0 + nn < N) v = src[(size_t)(k0 + kk) * N + n0 + nn];
;     if (ksc) v *= ksc[k0 + kk];
;     tl[kk * 65 + nn] = v;
;   }
;   __syncthreads();
.LBB0_156:
	s_andn2_b64 vcc, exec, s[4:5]
	s_cbranch_vccnz .LBB0_177
	s_add_i32 s7, s97, 0xfffff9e8
	s_lshl_b64 s[4:5], s[54:55], 20
	s_waitcnt lgkmcnt(0)
	s_add_u32 s48, s18, s4
	v_mov_b32_e32 v1, v163
	s_mov_b32 s4, s2
	s_addc_u32 s58, s19, s5
	s_lshr_b32 s6, s7, 4
	s_lshl_b32 s4, s6, 10
	s_lshl_b32 s5, s7, 6
	s_sub_i32 s4, s5, s4
	v_and_b32_e32 v6, 63, v1
	s_ashr_i32 s5, s4, 31
	v_ashrrev_i32_e32 v7, 6, v1
	v_or_b32_e32 v1, s4, v6
	s_lshl_b64 s[4:5], s[4:5], 2
	s_add_u32 s4, s48, s4
	s_addc_u32 s5, s58, s5
	v_lshlrev_b32_e32 v2, 2, v6
	v_lshl_add_u64 v[4:5], s[4:5], 0, v[2:3]
	v_mad_u64_u32 v[8:9], s[4:5], v7, s82, v[2:3]
	s_mul_i32 s4, s54, 0xf70
	s_sub_i32 s4, s74, s4
	s_lshr_b32 s7, s4, 4
	v_cmp_gt_i32_e32 vcc, s83, v1
	v_lshl_add_u32 v1, s7, 6, v7
	s_mov_b32 s48, 0
	s_barrier
	s_branch .LBB0_159
.LBB0_159:
	v_mov_b32_e32 v16, 0
	v_mov_b32_e32 v17, 0
	v_mov_b32_e32 v18, 0
	v_mov_b32_e32 v19, 0
	v_mov_b32_e32 v20, 0
	v_mov_b32_e32 v21, 0
	v_mov_b32_e32 v22, 0
	v_mov_b32_e32 v23, 0
	v_mov_b32_e32 v24, 0
	v_mov_b32_e32 v25, 0
	v_mov_b32_e32 v26, 0
	v_mov_b32_e32 v27, 0
	v_mov_b32_e32 v28, 0
	v_mov_b32_e32 v29, 0
	v_mov_b32_e32 v30, 0
	v_mov_b32_e32 v31, 0
	s_and_saveexec_b64 s[4:5], vcc
	s_cbranch_execz .Lprep_brr_done
	v_mov_b32_e32 v10, v1
	v_ashrrev_i32_e32 v11, 31, v10
	v_lshlrev_b64 v[10:11], 12, v[10:11]
	v_lshl_add_u64 v[10:11], v[4:5], 0, v[10:11]
	global_load_dword v16, v[10:11], off
	v_add_u32_e32 v10, 4, v1
	v_ashrrev_i32_e32 v11, 31, v10
	v_lshlrev_b64 v[10:11], 12, v[10:11]
	v_lshl_add_u64 v[10:11], v[4:5], 0, v[10:11]
	global_load_dword v17, v[10:11], off
	v_add_u32_e32 v10, 8, v1
	v_ashrrev_i32_e32 v11, 31, v10
	v_lshlrev_b64 v[10:11], 12, v[10:11]
	v_lshl_add_u64 v[10:11], v[4:5], 0, v[10:11]
	global_load_dword v18, v[10:11], off
	v_add_u32_e32 v10, 12, v1
	v_ashrrev_i32_e32 v11, 31, v10
	v_lshlrev_b64 v[10:11], 12, v[10:11]
	v_lshl_add_u64 v[10:11], v[4:5], 0, v[10:11]
	global_load_dword v19, v[10:11], off
	v_add_u32_e32 v10, 16, v1
	v_ashrrev_i32_e32 v11, 31, v10
	v_lshlrev_b64 v[10:11], 12, v[10:11]
	v_lshl_add_u64 v[10:11], v[4:5], 0, v[10:11]
	global_load_dword v20, v[10:11], off
	v_add_u32_e32 v10, 20, v1
	v_ashrrev_i32_e32 v11, 31, v10
	v_lshlrev_b64 v[10:11], 12, v[10:11]
	v_lshl_add_u64 v[10:11], v[4:5], 0, v[10:11]
	global_load_dword v21, v[10:11], off
	v_add_u32_e32 v10, 24, v1
	v_ashrrev_i32_e32 v11, 31, v10
	v_lshlrev_b64 v[10:11], 12, v[10:11]
	v_lshl_add_u64 v[10:11], v[4:5], 0, v[10:11]
	global_load_dword v22, v[10:11], off
	v_add_u32_e32 v10, 28, v1
	v_ashrrev_i32_e32 v11, 31, v10
	v_lshlrev_b64 v[10:11], 12, v[10:11]
	v_lshl_add_u64 v[10:11], v[4:5], 0, v[10:11]
	global_load_dword v23, v[10:11], off
	v_add_u32_e32 v10, 32, v1
	v_ashrrev_i32_e32 v11, 31, v10
	v_lshlrev_b64 v[10:11], 12, v[10:11]
	v_lshl_add_u64 v[10:11], v[4:5], 0, v[10:11]
	global_load_dword v24, v[10:11], off
	v_add_u32_e32 v10, 36, v1
	v_ashrrev_i32_e32 v11, 31, v10
	v_lshlrev_b64 v[10:11], 12, v[10:11]
	v_lshl_add_u64 v[10:11], v[4:5], 0, v[10:11]
	global_load_dword v25, v[10:11], off
	v_add_u32_e32 v10, 40, v1
	v_ashrrev_i32_e32 v11, 31, v10
	v_lshlrev_b64 v[10:11], 12, v[10:11]
	v_lshl_add_u64 v[10:11], v[4:5], 0, v[10:11]
	global_load_dword v26, v[10:11], off
	v_add_u32_e32 v10, 44, v1
	v_ashrrev_i32_e32 v11, 31, v10
	v_lshlrev_b64 v[10:11], 12, v[10:11]
	v_lshl_add_u64 v[10:11], v[4:5], 0, v[10:11]
	global_load_dword v27, v[10:11], off
	v_add_u32_e32 v10, 48, v1
	v_ashrrev_i32_e32 v11, 31, v10
	v_lshlrev_b64 v[10:11], 12, v[10:11]
	v_lshl_add_u64 v[10:11], v[4:5], 0, v[10:11]
	global_load_dword v28, v[10:11], off
	v_add_u32_e32 v10, 52, v1
	v_ashrrev_i32_e32 v11, 31, v10
	v_lshlrev_b64 v[10:11], 12, v[10:11]
	v_lshl_add_u64 v[10:11], v[4:5], 0, v[10:11]
	global_load_dword v29, v[10:11], off
	v_add_u32_e32 v10, 56, v1
	v_ashrrev_i32_e32 v11, 31, v10
	v_lshlrev_b64 v[10:11], 12, v[10:11]
	v_lshl_add_u64 v[10:11], v[4:5], 0, v[10:11]
	global_load_dword v30, v[10:11], off
	v_add_u32_e32 v10, 60, v1
	v_ashrrev_i32_e32 v11, 31, v10
	v_lshlrev_b64 v[10:11], 12, v[10:11]
	v_lshl_add_u64 v[10:11], v[4:5], 0, v[10:11]
	global_load_dword v31, v[10:11], off
.Lprep_brr_done:
	s_or_b64 exec, exec, s[4:5]
	s_waitcnt vmcnt(0)
	ds_write_b32 v8, v16
	ds_write_b32 v8, v17 offset:1040
	ds_write_b32 v8, v18 offset:2080
	ds_write_b32 v8, v19 offset:3120
	ds_write_b32 v8, v20 offset:4160
	ds_write_b32 v8, v21 offset:5200
	ds_write_b32 v8, v22 offset:6240
	ds_write_b32 v8, v23 offset:7280
	ds_write_b32 v8, v24 offset:8320
	ds_write_b32 v8, v25 offset:9360
	ds_write_b32 v8, v26 offset:10400
	ds_write_b32 v8, v27 offset:11440
	ds_write_b32 v8, v28 offset:12480
	ds_write_b32 v8, v29 offset:13520
	ds_write_b32 v8, v30 offset:14560
	ds_write_b32 v8, v31 offset:15600
.LBB0_167:
	s_lshl_b32 s4, s6, 7
	s_add_u32 s4, s56, s4
	s_addc_u32 s5, s57, 0
	v_lshlrev_b32_e32 v2, 1, v6
	v_lshl_add_u64 v[4:5], s[4:5], 0, v[2:3]
	s_mov_b64 s[4:5], 0xca0000
	v_lshl_add_u64 v[4:5], v[4:5], 0, s[4:5]
	v_add_u32_e32 v1, s66, v7
	s_lshl_b32 s4, s7, 10
	v_subrev_u32_e32 v1, s4, v1
	s_mul_i32 s4, s54, 0x3dc00
	v_lshlrev_b32_e32 v2, 2, v7
	v_subrev_u32_e32 v1, s4, v1
	v_mad_u32_u24 v2, v6, s82, v2
	s_mov_b32 s6, 0
	s_waitcnt lgkmcnt(0)
	s_barrier
	s_branch .LBB0_169

; #define LAUNDER_IDS const int tid__ = launder_v((int)threadIdx.x); const int blk__ = launder_s((int)blockIdx.x); (void)tid__; (void)blk__;
; DI void do_transpose(const float* __restrict__ src, int K, int N, u16* __restrict__ dst, const float* __restrict__ ksc, int perm, int tile, float* tl) {
;   LAUNDER_IDS
;   const int ntn = (N + 63) >> 6;
;   const int kt = tile / ntn, nt = tile - kt * ntn;
;   const int k0 = kt * 64, n0 = nt * 64;
;   const int tid = tid__;
;   __syncthreads();
; #pragma unroll 4
;   for (int i = 0; i < 16; ++i) {
;     const int kk = i * 4 + (tid >> 6), nn = tid & 63;
;     float v = 0.f;
;     if (n0 + nn < N) v = src[(size_t)(k0 + kk) * N + n0 + nn];
;     if (ksc) v *= ksc[k0 + kk];
;     tl[kk * 65 + nn] = v;
;   }
;   __syncthreads();
.LBB0_178:
	s_andn2_b64 vcc, exec, s[4:5]
	s_cbranch_vccnz .LBB0_199
	s_add_i32 s7, s97, 0xfffffa68
	s_lshl_b64 s[4:5], s[54:55], 21
	s_waitcnt lgkmcnt(0)
	s_add_u32 s48, s16, s4
	v_mov_b32_e32 v1, v163
	s_mov_b32 s4, s2
	s_addc_u32 s58, s17, s5
	s_lshr_b32 s6, s7, 4
	s_lshl_b32 s4, s6, 10
	s_lshl_b32 s5, s7, 6
	s_sub_i32 s4, s5, s4
	v_and_b32_e32 v6, 63, v1
	s_ashr_i32 s5, s4, 31
	v_ashrrev_i32_e32 v7, 6, v1
	v_or_b32_e32 v1, s4, v6
	s_lshl_b64 s[4:5], s[4:5], 2
	s_add_u32 s4, s48, s4
	s_addc_u32 s5, s58, s5
	v_lshlrev_b32_e32 v2, 2, v6
	v_lshl_add_u64 v[4:5], s[4:5], 0, v[2:3]
	v_mad_u64_u32 v[8:9], s[4:5], v7, s82, v[2:3]
	s_mul_i32 s4, s54, 0xf70
	s_sub_i32 s4, s75, s4
	s_lshr_b32 s7, s4, 4
	v_cmp_gt_i32_e32 vcc, s83, v1
	v_lshl_add_u32 v1, s7, 6, v7
	s_mov_b32 s48, 0
	s_barrier
	s_branch .LBB0_181
.LBB0_181:
	v_mov_b32_e32 v16, 0
	v_mov_b32_e32 v17, 0
	v_mov_b32_e32 v18, 0
	v_mov_b32_e32 v19, 0
	v_mov_b32_e32 v20, 0
	v_mov_b32_e32 v21, 0
	v_mov_b32_e32 v22, 0
	v_mov_b32_e32 v23, 0
	v_mov_b32_e32 v24, 0
	v_mov_b32_e32 v25, 0
	v_mov_b32_e32 v26, 0
	v_mov_b32_e32 v27, 0
	v_mov_b32_e32 v28, 0
	v_mov_b32_e32 v29, 0
	v_mov_b32_e32 v30, 0
	v_mov_b32_e32 v31, 0
	s_and_saveexec_b64 s[4:5], vcc
	s_cbranch_execz .Lprep_brm_done
	v_mov_b32_e32 v10, v1
	v_ashrrev_i32_e32 v11, 31, v10
	v_lshlrev_b64 v[10:11], 12, v[10:11]
	v_lshl_add_u64 v[10:11], v[4:5], 0, v[10:11]
	global_load_dword v16, v[10:11], off
	v_add_u32_e32 v10, 4, v1
	v_ashrrev_i32_e32 v11, 31, v10
	v_lshlrev_b64 v[10:11], 12, v[10:11]
	v_lshl_add_u64 v[10:11], v[4:5], 0, v[10:11]
	global_load_dword v17, v[10:11], off
	v_add_u32_e32 v10, 8, v1
	v_ashrrev_i32_e32 v11, 31, v10
	v_lshlrev_b64 v[10:11], 12, v[10:11]
	v_lshl_add_u64 v[10:11], v[4:5], 0, v[10:11]
	global_load_dword v18, v[10:11], off
	v_add_u32_e32 v10, 12, v1
	v_ashrrev_i32_e32 v11, 31, v10
	v_lshlrev_b64 v[10:11], 12, v[10:11]
	v_lshl_add_u64 v[10:11], v[4:5], 0, v[10:11]
	global_load_dword v19, v[10:11], off
	v_add_u32_e32 v10, 16, v1
	v_ashrrev_i32_e32 v11, 31, v10
	v_lshlrev_b64 v[10:11], 12, v[10:11]
	v_lshl_add_u64 v[10:11], v[4:5], 0, v[10:11]
	global_load_dword v20, v[10:11], off
	v_add_u32_e32 v10, 20, v1
	v_ashrrev_i32_e32 v11, 31, v10
	v_lshlrev_b64 v[10:11], 12, v[10:11]
	v_lshl_add_u64 v[10:11], v[4:5], 0, v[10:11]
	global_load_dword v21, v[10:11], off
	v_add_u32_e32 v10, 24, v1
	v_ashrrev_i32_e32 v11, 31, v10
	v_lshlrev_b64 v[10:11], 12, v[10:11]
	v_lshl_add_u64 v[10:11], v[4:5], 0, v[10:11]
	global_load_dword v22, v[10:11], off
	v_add_u32_e32 v10, 28, v1
	v_ashrrev_i32_e32 v11, 31, v10
	v_lshlrev_b64 v[10:11], 12, v[10:11]
	v_lshl_add_u64 v[10:11], v[4:5], 0, v[10:11]
	global_load_dword v23, v[10:11], off
	v_add_u32_e32 v10, 32, v1
	v_ashrrev_i32_e32 v11, 31, v10
	v_lshlrev_b64 v[10:11], 12, v[10:11]
	v_lshl_add_u64 v[10:11], v[4:5], 0, v[10:11]
	global_load_dword v24, v[10:11], off
	v_add_u32_e32 v10, 36, v1
	v_ashrrev_i32_e32 v11, 31, v10
	v_lshlrev_b64 v[10:11], 12, v[10:11]
	v_lshl_add_u64 v[10:11], v[4:5], 0, v[10:11]
	global_load_dword v25, v[10:11], off
	v_add_u32_e32 v10, 40, v1
	v_ashrrev_i32_e32 v11, 31, v10
	v_lshlrev_b64 v[10:11], 12, v[10:11]
	v_lshl_add_u64 v[10:11], v[4:5], 0, v[10:11]
	global_load_dword v26, v[10:11], off
	v_add_u32_e32 v10, 44, v1
	v_ashrrev_i32_e32 v11, 31, v10
	v_lshlrev_b64 v[10:11], 12, v[10:11]
	v_lshl_add_u64 v[10:11], v[4:5], 0, v[10:11]
	global_load_dword v27, v[10:11], off
	v_add_u32_e32 v10, 48, v1
	v_ashrrev_i32_e32 v11, 31, v10
	v_lshlrev_b64 v[10:11], 12, v[10:11]
	v_lshl_add_u64 v[10:11], v[4:5], 0, v[10:11]
	global_load_dword v28, v[10:11], off
	v_add_u32_e32 v10, 52, v1
	v_ashrrev_i32_e32 v11, 31, v10
	v_lshlrev_b64 v[10:11], 12, v[10:11]
	v_lshl_add_u64 v[10:11], v[4:5], 0, v[10:11]
	global_load_dword v29, v[10:11], off
	v_add_u32_e32 v10, 56, v1
	v_ashrrev_i32_e32 v11, 31, v10
	v_lshlrev_b64 v[10:11], 12, v[10:11]
	v_lshl_add_u64 v[10:11], v[4:5], 0, v[10:11]
	global_load_dword v30, v[10:11], off
	v_add_u32_e32 v10, 60, v1
	v_ashrrev_i32_e32 v11, 31, v10
	v_lshlrev_b64 v[10:11], 12, v[10:11]
	v_lshl_add_u64 v[10:11], v[4:5], 0, v[10:11]
	global_load_dword v31, v[10:11], off
.Lprep_brm_done:
	s_or_b64 exec, exec, s[4:5]
	s_waitcnt vmcnt(0)
	ds_write_b32 v8, v16
	ds_write_b32 v8, v17 offset:1040
	ds_write_b32 v8, v18 offset:2080
	ds_write_b32 v8, v19 offset:3120
	ds_write_b32 v8, v20 offset:4160
	ds_write_b32 v8, v21 offset:5200
	ds_write_b32 v8, v22 offset:6240
	ds_write_b32 v8, v23 offset:7280
	ds_write_b32 v8, v24 offset:8320
	ds_write_b32 v8, v25 offset:9360
	ds_write_b32 v8, v26 offset:10400
	ds_write_b32 v8, v27 offset:11440
	ds_write_b32 v8, v28 offset:12480
	ds_write_b32 v8, v29 offset:13520
	ds_write_b32 v8, v30 offset:14560
	ds_write_b32 v8, v31 offset:15600
.LBB0_189:
	s_lshl_b32 s4, s6, 7
	s_add_u32 s4, s56, s4
	s_addc_u32 s5, s57, 0
	v_lshlrev_b32_e32 v2, 1, v6
	v_lshl_add_u64 v[4:5], s[4:5], 0, v[2:3]
	s_mov_b64 s[4:5], 0xba0000
	v_lshl_add_u64 v[4:5], v[4:5], 0, s[4:5]
	v_add_u32_e32 v1, s66, v7
	s_lshl_b32 s4, s7, 10
	v_subrev_u32_e32 v1, s4, v1
	s_mul_i32 s4, s54, 0x3dc00
	v_lshlrev_b32_e32 v2, 2, v7
	v_subrev_u32_e32 v1, s4, v1
	v_mad_u32_u24 v2, v6, s82, v2
	s_mov_b32 s6, 0
	s_waitcnt lgkmcnt(0)
	s_barrier
	s_branch .LBB0_191

; DI void do_transpose(const float* __restrict__ src, int K, int N, u16* __restrict__ dst, const float* __restrict__ ksc, int perm, int tile, float* tl) {
;     ...
;   __syncthreads();
; #pragma unroll 4
;   for (int i = 0; i < 16; ++i) {
;     const int kk = i * 4 + (tid >> 6), nn = tid & 63;
;     float v = 0.f;
;     if (n0 + nn < N) v = src[(size_t)(k0 + kk) * N + n0 + nn];
;     if (ksc) v *= ksc[k0 + kk];
;     tl[kk * 65 + nn] = v;
;   }
.LBB0_203:
	v_mov_b32_e32 v200, 0
	v_mov_b32_e32 v201, 0
	v_mov_b32_e32 v202, 0
	v_mov_b32_e32 v203, 0
	v_mov_b32_e32 v204, 0
	v_mov_b32_e32 v205, 0
	v_mov_b32_e32 v206, 0
	v_mov_b32_e32 v207, 0
	v_mov_b32_e32 v208, 0
	v_mov_b32_e32 v209, 0
	v_mov_b32_e32 v210, 0
	v_mov_b32_e32 v211, 0
	v_mov_b32_e32 v212, 0
	v_mov_b32_e32 v213, 0
	v_mov_b32_e32 v214, 0
	v_mov_b32_e32 v215, 0
	s_and_saveexec_b64 s[4:5], s[6:7]
	s_cbranch_execz .Lprep_ukv_d
	v_mov_b32_e32 v16, v1
	v_ashrrev_i32_e32 v17, 31, v16
	v_lshlrev_b64 v[16:17], 12, v[16:17]
	v_lshl_add_u64 v[16:17], v[8:9], 0, v[16:17]
	global_load_dword v200, v[16:17], off
	v_add_u32_e32 v16, 4, v1
	v_ashrrev_i32_e32 v17, 31, v16
	v_lshlrev_b64 v[16:17], 12, v[16:17]
	v_lshl_add_u64 v[16:17], v[8:9], 0, v[16:17]
	global_load_dword v201, v[16:17], off
	v_add_u32_e32 v16, 8, v1
	v_ashrrev_i32_e32 v17, 31, v16
	v_lshlrev_b64 v[16:17], 12, v[16:17]
	v_lshl_add_u64 v[16:17], v[8:9], 0, v[16:17]
	global_load_dword v202, v[16:17], off
	v_add_u32_e32 v16, 12, v1
	v_ashrrev_i32_e32 v17, 31, v16
	v_lshlrev_b64 v[16:17], 12, v[16:17]
	v_lshl_add_u64 v[16:17], v[8:9], 0, v[16:17]
	global_load_dword v203, v[16:17], off
	v_add_u32_e32 v16, 16, v1
	v_ashrrev_i32_e32 v17, 31, v16
	v_lshlrev_b64 v[16:17], 12, v[16:17]
	v_lshl_add_u64 v[16:17], v[8:9], 0, v[16:17]
	global_load_dword v204, v[16:17], off
	v_add_u32_e32 v16, 20, v1
	v_ashrrev_i32_e32 v17, 31, v16
	v_lshlrev_b64 v[16:17], 12, v[16:17]
	v_lshl_add_u64 v[16:17], v[8:9], 0, v[16:17]
	global_load_dword v205, v[16:17], off
	v_add_u32_e32 v16, 24, v1
	v_ashrrev_i32_e32 v17, 31, v16
	v_lshlrev_b64 v[16:17], 12, v[16:17]
	v_lshl_add_u64 v[16:17], v[8:9], 0, v[16:17]
	global_load_dword v206, v[16:17], off
	v_add_u32_e32 v16, 28, v1
	v_ashrrev_i32_e32 v17, 31, v16
	v_lshlrev_b64 v[16:17], 12, v[16:17]
	v_lshl_add_u64 v[16:17], v[8:9], 0, v[16:17]
	global_load_dword v207, v[16:17], off
	v_add_u32_e32 v16, 32, v1
	v_ashrrev_i32_e32 v17, 31, v16
	v_lshlrev_b64 v[16:17], 12, v[16:17]
	v_lshl_add_u64 v[16:17], v[8:9], 0, v[16:17]
	global_load_dword v208, v[16:17], off
	v_add_u32_e32 v16, 36, v1
	v_ashrrev_i32_e32 v17, 31, v16
	v_lshlrev_b64 v[16:17], 12, v[16:17]
	v_lshl_add_u64 v[16:17], v[8:9], 0, v[16:17]
	global_load_dword v209, v[16:17], off
	v_add_u32_e32 v16, 40, v1
	v_ashrrev_i32_e32 v17, 31, v16
	v_lshlrev_b64 v[16:17], 12, v[16:17]
	v_lshl_add_u64 v[16:17], v[8:9], 0, v[16:17]
	global_load_dword v210, v[16:17], off
	v_add_u32_e32 v16, 44, v1
	v_ashrrev_i32_e32 v17, 31, v16
	v_lshlrev_b64 v[16:17], 12, v[16:17]
	v_lshl_add_u64 v[16:17], v[8:9], 0, v[16:17]
	global_load_dword v211, v[16:17], off
	v_add_u32_e32 v16, 48, v1
	v_ashrrev_i32_e32 v17, 31, v16
	v_lshlrev_b64 v[16:17], 12, v[16:17]
	v_lshl_add_u64 v[16:17], v[8:9], 0, v[16:17]
	global_load_dword v212, v[16:17], off
	v_add_u32_e32 v16, 52, v1
	v_ashrrev_i32_e32 v17, 31, v16
	v_lshlrev_b64 v[16:17], 12, v[16:17]
	v_lshl_add_u64 v[16:17], v[8:9], 0, v[16:17]
	global_load_dword v213, v[16:17], off
	v_add_u32_e32 v16, 56, v1
	v_ashrrev_i32_e32 v17, 31, v16
	v_lshlrev_b64 v[16:17], 12, v[16:17]
	v_lshl_add_u64 v[16:17], v[8:9], 0, v[16:17]
	global_load_dword v214, v[16:17], off
	v_add_u32_e32 v16, 60, v1
	v_ashrrev_i32_e32 v17, 31, v16
	v_lshlrev_b64 v[16:17], 12, v[16:17]
	v_lshl_add_u64 v[16:17], v[8:9], 0, v[16:17]
	global_load_dword v215, v[16:17], off
.Lprep_ukv_d:
	s_or_b64 exec, exec, s[4:5]
	s_andn2_b64 vcc, exec, s[42:43]
	s_cbranch_vccnz .Lprep_ukv_ns
	v_mov_b32_e32 v16, v1
	v_ashrrev_i32_e32 v17, 31, v16
	v_lshl_add_u64 v[16:17], v[16:17], 2, s[58:59]
	global_load_dword v216, v[16:17], off
	global_load_dword v217, v[12:13], off offset:-16
	global_load_dword v218, v[12:13], off
	global_load_dword v219, v[12:13], off offset:16
	v_add_u32_e32 v16, 16, v1
	v_ashrrev_i32_e32 v17, 31, v16
	v_lshl_add_u64 v[16:17], v[16:17], 2, s[58:59]
	global_load_dword v220, v[16:17], off
	global_load_dword v221, v[12:13], off offset:48
	global_load_dword v222, v[12:13], off offset:64
	global_load_dword v223, v[12:13], off offset:80
	v_add_u32_e32 v16, 32, v1
	v_ashrrev_i32_e32 v17, 31, v16
	v_lshl_add_u64 v[16:17], v[16:17], 2, s[58:59]
	global_load_dword v224, v[16:17], off
	global_load_dword v225, v[12:13], off offset:112
	global_load_dword v226, v[12:13], off offset:128
	global_load_dword v227, v[12:13], off offset:144
	v_add_u32_e32 v16, 48, v1
	v_ashrrev_i32_e32 v17, 31, v16
	v_lshl_add_u64 v[16:17], v[16:17], 2, s[58:59]
	global_load_dword v228, v[16:17], off
	global_load_dword v229, v[12:13], off offset:176
	global_load_dword v230, v[12:13], off offset:192
	global_load_dword v231, v[12:13], off offset:208
	s_waitcnt vmcnt(0)
	v_mul_f32_e32 v200, v200, v216
	v_mul_f32_e32 v201, v201, v217
	v_mul_f32_e32 v202, v202, v218
	v_mul_f32_e32 v203, v203, v219
	v_mul_f32_e32 v204, v204, v220
	v_mul_f32_e32 v205, v205, v221
	v_mul_f32_e32 v206, v206, v222
	v_mul_f32_e32 v207, v207, v223
	v_mul_f32_e32 v208, v208, v224
	v_mul_f32_e32 v209, v209, v225
	v_mul_f32_e32 v210, v210, v226
	v_mul_f32_e32 v211, v211, v227
	v_mul_f32_e32 v212, v212, v228
	v_mul_f32_e32 v213, v213, v229
	v_mul_f32_e32 v214, v214, v230
	v_mul_f32_e32 v215, v215, v231
.Lprep_ukv_ns:
	s_waitcnt vmcnt(0)
	ds_write_b32 v10, v200
	ds_write_b32 v10, v201 offset:1040
	ds_write_b32 v10, v202 offset:2080
	ds_write_b32 v10, v203 offset:3120
	ds_write_b32 v10, v204 offset:4160
	ds_write_b32 v10, v205 offset:5200
	ds_write_b32 v10, v206 offset:6240
	ds_write_b32 v10, v207 offset:7280
	ds_write_b32 v10, v208 offset:8320
	ds_write_b32 v10, v209 offset:9360
	ds_write_b32 v10, v210 offset:10400
	ds_write_b32 v10, v211 offset:11440
	ds_write_b32 v10, v212 offset:12480
	ds_write_b32 v10, v213 offset:13520
	ds_write_b32 v10, v214 offset:14560
	ds_write_b32 v10, v215 offset:15600

; DI void do_transpose(const float* __restrict__ src, int K, int N, u16* __restrict__ dst, const float* __restrict__ ksc, int perm, int tile, float* tl) {
;     ...
;   __syncthreads();
; #pragma unroll 4
;   for (int i = 0; i < 16; ++i) {
;     const int kk = i * 4 + (tid >> 6), nn = tid & 63;
;     float v = 0.f;
;     if (n0 + nn < N) v = src[(size_t)(k0 + kk) * N + n0 + nn];
;     if (ksc) v *= ksc[k0 + kk];
;     tl[kk * 65 + nn] = v;
;   }
.LBB0_233:
	v_mov_b32_e32 v200, 0
	v_mov_b32_e32 v201, 0
	v_mov_b32_e32 v202, 0
	v_mov_b32_e32 v203, 0
	v_mov_b32_e32 v204, 0
	v_mov_b32_e32 v205, 0
	v_mov_b32_e32 v206, 0
	v_mov_b32_e32 v207, 0
	v_mov_b32_e32 v208, 0
	v_mov_b32_e32 v209, 0
	v_mov_b32_e32 v210, 0
	v_mov_b32_e32 v211, 0
	v_mov_b32_e32 v212, 0
	v_mov_b32_e32 v213, 0
	v_mov_b32_e32 v214, 0
	v_mov_b32_e32 v215, 0
	s_and_saveexec_b64 s[4:5], s[6:7]
	s_cbranch_execz .Lprep_uq_d
	v_lshl_add_u64 v[24:25], v[20:21], 0, s[62:63]
	global_load_dword v200, v[24:25], off
	v_lshl_add_u64 v[24:25], v[18:19], 0, s[62:63]
	global_load_dword v201, v[24:25], off
	v_lshl_add_u64 v[24:25], v[16:17], 0, s[62:63]
	global_load_dword v202, v[24:25], off
	v_lshl_add_u64 v[24:25], v[10:11], 0, s[62:63]
	global_load_dword v203, v[24:25], off
	s_add_u32 s62, s62, 0xc000
	s_addc_u32 s63, s63, 0
	v_lshl_add_u64 v[24:25], v[20:21], 0, s[62:63]
	global_load_dword v204, v[24:25], off
	v_lshl_add_u64 v[24:25], v[18:19], 0, s[62:63]
	global_load_dword v205, v[24:25], off
	v_lshl_add_u64 v[24:25], v[16:17], 0, s[62:63]
	global_load_dword v206, v[24:25], off
	v_lshl_add_u64 v[24:25], v[10:11], 0, s[62:63]
	global_load_dword v207, v[24:25], off
	s_add_u32 s62, s62, 0xc000
	s_addc_u32 s63, s63, 0
	v_lshl_add_u64 v[24:25], v[20:21], 0, s[62:63]
	global_load_dword v208, v[24:25], off
	v_lshl_add_u64 v[24:25], v[18:19], 0, s[62:63]
	global_load_dword v209, v[24:25], off
	v_lshl_add_u64 v[24:25], v[16:17], 0, s[62:63]
	global_load_dword v210, v[24:25], off
	v_lshl_add_u64 v[24:25], v[10:11], 0, s[62:63]
	global_load_dword v211, v[24:25], off
	s_add_u32 s62, s62, 0xc000
	s_addc_u32 s63, s63, 0
	v_lshl_add_u64 v[24:25], v[20:21], 0, s[62:63]
	global_load_dword v212, v[24:25], off
	v_lshl_add_u64 v[24:25], v[18:19], 0, s[62:63]
	global_load_dword v213, v[24:25], off
	v_lshl_add_u64 v[24:25], v[16:17], 0, s[62:63]
	global_load_dword v214, v[24:25], off
	v_lshl_add_u64 v[24:25], v[10:11], 0, s[62:63]
	global_load_dword v215, v[24:25], off
	s_add_u32 s62, s62, 0xc000
	s_addc_u32 s63, s63, 0
.Lprep_uq_d:
	s_or_b64 exec, exec, s[4:5]
	s_andn2_b64 vcc, exec, s[44:45]
	s_cbranch_vccnz .Lprep_uq_ns
	v_lshl_add_u64 v[26:27], v[22:23], 0, s[60:61]
	v_lshl_add_u64 v[24:25], v[12:13], 0, s[60:61]
	global_load_dword v216, v[26:27], off
	global_load_dword v217, v[24:25], off offset:16
	global_load_dword v218, v[24:25], off offset:32
	global_load_dword v219, v[24:25], off offset:48
	global_load_dword v220, v[26:27], off offset:64
	global_load_dword v221, v[24:25], off offset:80
	global_load_dword v222, v[24:25], off offset:96
	global_load_dword v223, v[24:25], off offset:112
	global_load_dword v224, v[26:27], off offset:128
	global_load_dword v225, v[24:25], off offset:144
	global_load_dword v226, v[24:25], off offset:160
	global_load_dword v227, v[24:25], off offset:176
	global_load_dword v228, v[26:27], off offset:192
	global_load_dword v229, v[24:25], off offset:208
	global_load_dword v230, v[24:25], off offset:224
	global_load_dword v231, v[24:25], off offset:240
	s_waitcnt vmcnt(0)
	v_mul_f32_e32 v200, v200, v216
	v_mul_f32_e32 v201, v201, v217
	v_mul_f32_e32 v202, v202, v218
	v_mul_f32_e32 v203, v203, v219
	v_mul_f32_e32 v204, v204, v220
	v_mul_f32_e32 v205, v205, v221
	v_mul_f32_e32 v206, v206, v222
	v_mul_f32_e32 v207, v207, v223
	v_mul_f32_e32 v208, v208, v224
	v_mul_f32_e32 v209, v209, v225
	v_mul_f32_e32 v210, v210, v226
	v_mul_f32_e32 v211, v211, v227
	v_mul_f32_e32 v212, v212, v228
	v_mul_f32_e32 v213, v213, v229
	v_mul_f32_e32 v214, v214, v230
	v_mul_f32_e32 v215, v215, v231
.Lprep_uq_ns:
	s_waitcnt vmcnt(0)
	ds_write_b32 v6, v200
	ds_write_b32 v6, v201 offset:1040
	ds_write_b32 v6, v202 offset:2080
	ds_write_b32 v6, v203 offset:3120
	ds_write_b32 v6, v204 offset:4160
	ds_write_b32 v6, v205 offset:5200
	ds_write_b32 v6, v206 offset:6240
	ds_write_b32 v6, v207 offset:7280
	ds_write_b32 v6, v208 offset:8320
	ds_write_b32 v6, v209 offset:9360
	ds_write_b32 v6, v210 offset:10400
	ds_write_b32 v6, v211 offset:11440
	ds_write_b32 v6, v212 offset:12480
	ds_write_b32 v6, v213 offset:13520
	ds_write_b32 v6, v214 offset:14560
	ds_write_b32 v6, v215 offset:15600

; DI void phase_prep(const Params& p, char* smem) {
;     ...
; #pragma unroll 8
;       for (int k = wave * 256; k < wave * 256 + 256; ++k) {
;         const float w = wa[(size_t)k * 6144];
; #pragma unroll
;         for (int b = 0; b < 9; ++b) acc[b] += sl[b * 1024 + k] * w;
;       }
.LBB0_319:
	s_mul_hi_i32 s4, s3, 0x2aaaaaab
	s_lshr_b32 s5, s4, 31
	s_ashr_i32 s10, s4, 4
	s_add_i32 s10, s10, s5
	s_mul_i32 s11, s10, 0x1800
	v_subrev_u32_e32 v2, s11, v15
	v_ashrrev_i32_e32 v3, 31, v2
	v_lshlrev_b64 v[2:3], 2, v[2:3]
	v_mad_i64_i32 v[2:3], s[4:5], s10, v34, v[2:3]
	v_lshl_add_u64 v[22:23], v[20:21], 0, v[2:3]
	s_mov_b64 s[8:9], 0
	v_mov_b32_e32 v36, v32
	v_mov_b32_e32 v24, 0
	v_mov_b32_e32 v25, v17
	v_mov_b32_e32 v26, 0
	v_mov_b32_e32 v27, v17
	v_mov_b32_e32 v28, 0
	v_mov_b32_e32 v29, v17
	v_mov_b32_e32 v30, 0
	v_mov_b32_e32 v31, v17
	v_mov_b32_e32 v37, 0
	v_mov_b32_e32 v192, 0x6000
	v_mov_b32_e32 v193, 0
	v_mov_b32_e32 v194, 0xc000
	v_mov_b32_e32 v195, 0
	v_mov_b32_e32 v196, 0x12000
	v_mov_b32_e32 v197, 0
	v_mov_b32_e32 v198, 0x18000
	v_mov_b32_e32 v199, 0
	v_mov_b32_e32 v200, 0x1e000
	v_mov_b32_e32 v201, 0
	v_mov_b32_e32 v202, 0x24000
	v_mov_b32_e32 v203, 0
	v_mov_b32_e32 v204, 0x2a000
	v_mov_b32_e32 v205, 0
.LBB0_320:
	v_lshl_add_u64 v[98:99], v[22:23], 0, s[8:9]
	v_lshl_add_u64 v[102:103], v[98:99], 0, v[192:193]
	v_lshl_add_u64 v[104:105], v[98:99], 0, v[194:195]
	v_lshl_add_u64 v[106:107], v[98:99], 0, v[196:197]
	v_lshl_add_u64 v[108:109], v[98:99], 0, v[198:199]
	v_lshl_add_u64 v[110:111], v[98:99], 0, v[200:201]
	v_lshl_add_u64 v[112:113], v[98:99], 0, v[202:203]
	v_lshl_add_u64 v[206:207], v[98:99], 0, v[204:205]
	global_load_dword v128, v[98:99], off
	global_load_dword v130, v[102:103], off
	global_load_dword v132, v[104:105], off
	global_load_dword v134, v[106:107], off
	global_load_dword v136, v[108:109], off
	global_load_dword v138, v[110:111], off
	global_load_dword v140, v[112:113], off
	global_load_dword v142, v[206:207], off
	s_add_u32 s8, s8, 0x30000
	s_addc_u32 s9, s9, 0
	v_lshl_add_u64 v[98:99], v[22:23], 0, s[8:9]
	v_lshl_add_u64 v[102:103], v[98:99], 0, v[192:193]
	v_lshl_add_u64 v[104:105], v[98:99], 0, v[194:195]
	v_lshl_add_u64 v[106:107], v[98:99], 0, v[196:197]
	v_lshl_add_u64 v[108:109], v[98:99], 0, v[198:199]
	v_lshl_add_u64 v[110:111], v[98:99], 0, v[200:201]
	v_lshl_add_u64 v[112:113], v[98:99], 0, v[202:203]
	v_lshl_add_u64 v[206:207], v[98:99], 0, v[204:205]
	global_load_dword v144, v[98:99], off
	global_load_dword v146, v[102:103], off
	global_load_dword v148, v[104:105], off
	global_load_dword v150, v[106:107], off
	global_load_dword v152, v[108:109], off
	global_load_dword v154, v[110:111], off
	global_load_dword v156, v[112:113], off
	global_load_dword v158, v[206:207], off
	s_add_u32 s8, s8, 0x30000
	s_addc_u32 s9, s9, 0
	v_lshl_add_u64 v[98:99], v[22:23], 0, s[8:9]
	v_lshl_add_u64 v[102:103], v[98:99], 0, v[192:193]
	v_lshl_add_u64 v[104:105], v[98:99], 0, v[194:195]
	v_lshl_add_u64 v[106:107], v[98:99], 0, v[196:197]
	v_lshl_add_u64 v[108:109], v[98:99], 0, v[198:199]
	v_lshl_add_u64 v[110:111], v[98:99], 0, v[200:201]
	v_lshl_add_u64 v[112:113], v[98:99], 0, v[202:203]
	v_lshl_add_u64 v[206:207], v[98:99], 0, v[204:205]
	global_load_dword v160, v[98:99], off
	global_load_dword v162, v[102:103], off
	global_load_dword v164, v[104:105], off
	global_load_dword v166, v[106:107], off
	global_load_dword v168, v[108:109], off
	global_load_dword v170, v[110:111], off
	global_load_dword v172, v[112:113], off
	global_load_dword v174, v[206:207], off
	s_add_u32 s8, s8, 0x30000
	s_addc_u32 s9, s9, 0
	v_lshl_add_u64 v[98:99], v[22:23], 0, s[8:9]
	v_lshl_add_u64 v[102:103], v[98:99], 0, v[192:193]
	v_lshl_add_u64 v[104:105], v[98:99], 0, v[194:195]
	v_lshl_add_u64 v[106:107], v[98:99], 0, v[196:197]
	v_lshl_add_u64 v[108:109], v[98:99], 0, v[198:199]
	v_lshl_add_u64 v[110:111], v[98:99], 0, v[200:201]
	v_lshl_add_u64 v[112:113], v[98:99], 0, v[202:203]
	v_lshl_add_u64 v[206:207], v[98:99], 0, v[204:205]
	global_load_dword v176, v[98:99], off
	global_load_dword v178, v[102:103], off
	global_load_dword v180, v[104:105], off
	global_load_dword v182, v[106:107], off
	global_load_dword v184, v[108:109], off
	global_load_dword v186, v[110:111], off
	global_load_dword v188, v[112:113], off
	global_load_dword v190, v[206:207], off
	s_add_u32 s8, s8, 0x30000
	s_addc_u32 s9, s9, 0
	ds_read_b128 v[10:13], v36
	ds_read_b128 v[6:9], v36 offset:16
	ds_read_b128 v[2:5], v36 offset:4096
	ds_read_b128 v[38:41], v36 offset:4112
	ds_read_b128 v[42:45], v36 offset:8192
	ds_read_b128 v[46:49], v36 offset:8208
	ds_read_b128 v[50:53], v36 offset:12288
	ds_read_b128 v[54:57], v36 offset:12304
	ds_read_b128 v[58:61], v36 offset:16384
	ds_read_b128 v[62:65], v36 offset:16400
	ds_read_b128 v[66:69], v36 offset:20480
	ds_read_b128 v[70:73], v36 offset:20496
	ds_read_b128 v[74:77], v36 offset:24576
	ds_read_b128 v[78:81], v36 offset:24592
	ds_read_b128 v[82:85], v36 offset:28672
	ds_read_b128 v[86:89], v36 offset:28688
	ds_read_b128 v[90:93], v36 offset:32768
	ds_read_b128 v[94:97], v36 offset:32784
	s_waitcnt vmcnt(24) lgkmcnt(1)
; DI void phase_prep(const Params& p, char* smem) {
;     ...
; #pragma unroll 8
;       for (int k = wave * 256; k < wave * 256 + 256; ++k) {
;         const float w = wa[(size_t)k * 6144];
; #pragma unroll
;         for (int b = 0; b < 9; ++b) acc[b] += sl[b * 1024 + k] * w;
;       }
	v_fmac_f32_e32 v37, v128, v90
	v_mov_b32_e32 v98, v10
	v_mov_b32_e32 v99, v2
	v_mov_b32_e32 v102, v42
	v_mov_b32_e32 v103, v50
	v_mov_b32_e32 v104, v58
	v_mov_b32_e32 v105, v66
	v_mov_b32_e32 v106, v74
	v_mov_b32_e32 v107, v82
	v_mov_b32_e32 v2, v11
	v_mov_b32_e32 v50, v43
	v_mov_b32_e32 v66, v59
	v_mov_b32_e32 v82, v75
	v_mov_b32_e32 v10, v12
	v_mov_b32_e32 v11, v4
	v_mov_b32_e32 v4, v13
	v_mov_b32_e32 v12, v6
	v_mov_b32_e32 v13, v38
	v_mov_b32_e32 v38, v7
	v_mov_b32_e32 v6, v8
	v_mov_b32_e32 v7, v40
	v_mov_b32_e32 v40, v9
	v_pk_fma_f32 v[8:9], v[128:129], v[98:99], v[24:25] op_sel_hi:[0,1,1]
	v_pk_fma_f32 v[24:25], v[128:129], v[102:103], v[26:27] op_sel_hi:[0,1,1]
	v_pk_fma_f32 v[26:27], v[128:129], v[104:105], v[28:29] op_sel_hi:[0,1,1]
	v_pk_fma_f32 v[28:29], v[128:129], v[106:107], v[30:31] op_sel_hi:[0,1,1]
	v_mov_b32_e32 v42, v44
	v_mov_b32_e32 v43, v52
	v_mov_b32_e32 v58, v60
	v_mov_b32_e32 v59, v68
	v_mov_b32_e32 v74, v76
	v_mov_b32_e32 v75, v84
	v_mov_b32_e32 v52, v45
	v_mov_b32_e32 v68, v61
	v_mov_b32_e32 v84, v77
	v_mov_b32_e32 v44, v46
	v_mov_b32_e32 v45, v54
	v_mov_b32_e32 v60, v62
	v_mov_b32_e32 v61, v70
	v_mov_b32_e32 v76, v78
	v_mov_b32_e32 v77, v86
	v_mov_b32_e32 v54, v47
	v_mov_b32_e32 v70, v63
	v_mov_b32_e32 v86, v79
	v_mov_b32_e32 v46, v48
	v_mov_b32_e32 v47, v56
	v_mov_b32_e32 v62, v64
	v_mov_b32_e32 v63, v72
	v_mov_b32_e32 v78, v80
	v_mov_b32_e32 v79, v88
	v_mov_b32_e32 v56, v49
	v_mov_b32_e32 v72, v65
	v_mov_b32_e32 v88, v81
	v_pk_fma_f32 v[2:3], v[130:131], v[2:3], v[8:9] op_sel_hi:[0,1,1]
	v_pk_fma_f32 v[8:9], v[130:131], v[50:51], v[24:25] op_sel_hi:[0,1,1]
	v_pk_fma_f32 v[24:25], v[130:131], v[66:67], v[26:27] op_sel_hi:[0,1,1]
	v_pk_fma_f32 v[26:27], v[130:131], v[82:83], v[28:29] op_sel_hi:[0,1,1]
	v_fmac_f32_e32 v37, v130, v91
	v_pk_fma_f32 v[2:3], v[132:133], v[10:11], v[2:3] op_sel_hi:[0,1,1]
	v_pk_fma_f32 v[8:9], v[132:133], v[42:43], v[8:9] op_sel_hi:[0,1,1]
	v_pk_fma_f32 v[10:11], v[132:133], v[58:59], v[24:25] op_sel_hi:[0,1,1]
	v_pk_fma_f32 v[24:25], v[132:133], v[74:75], v[26:27] op_sel_hi:[0,1,1]
	v_fmac_f32_e32 v37, v132, v92
	v_pk_fma_f32 v[2:3], v[134:135], v[4:5], v[2:3] op_sel_hi:[0,1,1]
	v_pk_fma_f32 v[4:5], v[134:135], v[52:53], v[8:9] op_sel_hi:[0,1,1]
	v_pk_fma_f32 v[8:9], v[134:135], v[68:69], v[10:11] op_sel_hi:[0,1,1]
	v_pk_fma_f32 v[10:11], v[134:135], v[84:85], v[24:25] op_sel_hi:[0,1,1]
	v_fmac_f32_e32 v37, v134, v93
	v_pk_fma_f32 v[2:3], v[136:137], v[12:13], v[2:3] op_sel_hi:[0,1,1]
	v_pk_fma_f32 v[4:5], v[136:137], v[44:45], v[4:5] op_sel_hi:[0,1,1]
	v_pk_fma_f32 v[8:9], v[136:137], v[60:61], v[8:9] op_sel_hi:[0,1,1]
	v_pk_fma_f32 v[10:11], v[136:137], v[76:77], v[10:11] op_sel_hi:[0,1,1]
	s_waitcnt lgkmcnt(0)
	v_fmac_f32_e32 v37, v136, v94
	v_pk_fma_f32 v[2:3], v[138:139], v[38:39], v[2:3] op_sel_hi:[0,1,1]
	v_pk_fma_f32 v[4:5], v[138:139], v[54:55], v[4:5] op_sel_hi:[0,1,1]
	v_pk_fma_f32 v[8:9], v[138:139], v[70:71], v[8:9] op_sel_hi:[0,1,1]
	v_pk_fma_f32 v[10:11], v[138:139], v[86:87], v[10:11] op_sel_hi:[0,1,1]
	v_fmac_f32_e32 v37, v138, v95
	v_pk_fma_f32 v[2:3], v[140:141], v[6:7], v[2:3] op_sel_hi:[0,1,1]
	v_pk_fma_f32 v[4:5], v[140:141], v[46:47], v[4:5] op_sel_hi:[0,1,1]
	v_pk_fma_f32 v[6:7], v[140:141], v[62:63], v[8:9] op_sel_hi:[0,1,1]
	v_pk_fma_f32 v[8:9], v[140:141], v[78:79], v[10:11] op_sel_hi:[0,1,1]
	v_fmac_f32_e32 v37, v140, v96
	v_pk_fma_f32 v[24:25], v[142:143], v[40:41], v[2:3] op_sel_hi:[0,1,1]
	v_pk_fma_f32 v[26:27], v[142:143], v[56:57], v[4:5] op_sel_hi:[0,1,1]
	v_pk_fma_f32 v[28:29], v[142:143], v[72:73], v[6:7] op_sel_hi:[0,1,1]
	v_pk_fma_f32 v[30:31], v[142:143], v[88:89], v[8:9] op_sel_hi:[0,1,1]
	v_fmac_f32_e32 v37, v142, v97
	ds_read_b128 v[10:13], v36 offset:32
	ds_read_b128 v[6:9], v36 offset:48
	ds_read_b128 v[2:5], v36 offset:4128
	ds_read_b128 v[38:41], v36 offset:4144
	ds_read_b128 v[42:45], v36 offset:8224
	ds_read_b128 v[46:49], v36 offset:8240
	ds_read_b128 v[50:53], v36 offset:12320
	ds_read_b128 v[54:57], v36 offset:12336
	ds_read_b128 v[58:61], v36 offset:16416
	ds_read_b128 v[62:65], v36 offset:16432
	ds_read_b128 v[66:69], v36 offset:20512
	ds_read_b128 v[70:73], v36 offset:20528
	ds_read_b128 v[74:77], v36 offset:24608
	ds_read_b128 v[78:81], v36 offset:24624
	ds_read_b128 v[82:85], v36 offset:28704
	ds_read_b128 v[86:89], v36 offset:28720
	ds_read_b128 v[90:93], v36 offset:32800
	ds_read_b128 v[94:97], v36 offset:32816
	s_waitcnt vmcnt(16) lgkmcnt(1)
; DI void phase_prep(const Params& p, char* smem) {
;     ...
; #pragma unroll 8
;       for (int k = wave * 256; k < wave * 256 + 256; ++k) {
;         const float w = wa[(size_t)k * 6144];
; #pragma unroll
;         for (int b = 0; b < 9; ++b) acc[b] += sl[b * 1024 + k] * w;
;       }
	v_fmac_f32_e32 v37, v144, v90
	v_mov_b32_e32 v98, v10
	v_mov_b32_e32 v99, v2
	v_mov_b32_e32 v102, v42
	v_mov_b32_e32 v103, v50
	v_mov_b32_e32 v104, v58
	v_mov_b32_e32 v105, v66
	v_mov_b32_e32 v106, v74
	v_mov_b32_e32 v107, v82
	v_mov_b32_e32 v2, v11
	v_mov_b32_e32 v50, v43
	v_mov_b32_e32 v66, v59
	v_mov_b32_e32 v82, v75
	v_mov_b32_e32 v10, v12
	v_mov_b32_e32 v11, v4
	v_mov_b32_e32 v4, v13
	v_mov_b32_e32 v12, v6
	v_mov_b32_e32 v13, v38
	v_mov_b32_e32 v38, v7
	v_mov_b32_e32 v6, v8
	v_mov_b32_e32 v7, v40
	v_mov_b32_e32 v40, v9
	v_pk_fma_f32 v[8:9], v[144:145], v[98:99], v[24:25] op_sel_hi:[0,1,1]
	v_pk_fma_f32 v[24:25], v[144:145], v[102:103], v[26:27] op_sel_hi:[0,1,1]
	v_pk_fma_f32 v[26:27], v[144:145], v[104:105], v[28:29] op_sel_hi:[0,1,1]
	v_pk_fma_f32 v[28:29], v[144:145], v[106:107], v[30:31] op_sel_hi:[0,1,1]
	v_mov_b32_e32 v42, v44
	v_mov_b32_e32 v43, v52
	v_mov_b32_e32 v58, v60
	v_mov_b32_e32 v59, v68
	v_mov_b32_e32 v74, v76
	v_mov_b32_e32 v75, v84
	v_mov_b32_e32 v52, v45
	v_mov_b32_e32 v68, v61
	v_mov_b32_e32 v84, v77
	v_mov_b32_e32 v44, v46
	v_mov_b32_e32 v45, v54
	v_mov_b32_e32 v60, v62
	v_mov_b32_e32 v61, v70
	v_mov_b32_e32 v76, v78
	v_mov_b32_e32 v77, v86
	v_mov_b32_e32 v54, v47
	v_mov_b32_e32 v70, v63
	v_mov_b32_e32 v86, v79
	v_mov_b32_e32 v46, v48
	v_mov_b32_e32 v47, v56
	v_mov_b32_e32 v62, v64
	v_mov_b32_e32 v63, v72
	v_mov_b32_e32 v78, v80
	v_mov_b32_e32 v79, v88
	v_mov_b32_e32 v56, v49
	v_mov_b32_e32 v72, v65
	v_mov_b32_e32 v88, v81
	v_pk_fma_f32 v[2:3], v[146:147], v[2:3], v[8:9] op_sel_hi:[0,1,1]
	v_pk_fma_f32 v[8:9], v[146:147], v[50:51], v[24:25] op_sel_hi:[0,1,1]
	v_pk_fma_f32 v[24:25], v[146:147], v[66:67], v[26:27] op_sel_hi:[0,1,1]
	v_pk_fma_f32 v[26:27], v[146:147], v[82:83], v[28:29] op_sel_hi:[0,1,1]
	v_fmac_f32_e32 v37, v146, v91
	v_pk_fma_f32 v[2:3], v[148:149], v[10:11], v[2:3] op_sel_hi:[0,1,1]
	v_pk_fma_f32 v[8:9], v[148:149], v[42:43], v[8:9] op_sel_hi:[0,1,1]
	v_pk_fma_f32 v[10:11], v[148:149], v[58:59], v[24:25] op_sel_hi:[0,1,1]
	v_pk_fma_f32 v[24:25], v[148:149], v[74:75], v[26:27] op_sel_hi:[0,1,1]
	v_fmac_f32_e32 v37, v148, v92
	v_pk_fma_f32 v[2:3], v[150:151], v[4:5], v[2:3] op_sel_hi:[0,1,1]
	v_pk_fma_f32 v[4:5], v[150:151], v[52:53], v[8:9] op_sel_hi:[0,1,1]
	v_pk_fma_f32 v[8:9], v[150:151], v[68:69], v[10:11] op_sel_hi:[0,1,1]
	v_pk_fma_f32 v[10:11], v[150:151], v[84:85], v[24:25] op_sel_hi:[0,1,1]
	v_fmac_f32_e32 v37, v150, v93
	v_pk_fma_f32 v[2:3], v[152:153], v[12:13], v[2:3] op_sel_hi:[0,1,1]
	v_pk_fma_f32 v[4:5], v[152:153], v[44:45], v[4:5] op_sel_hi:[0,1,1]
	v_pk_fma_f32 v[8:9], v[152:153], v[60:61], v[8:9] op_sel_hi:[0,1,1]
	v_pk_fma_f32 v[10:11], v[152:153], v[76:77], v[10:11] op_sel_hi:[0,1,1]
	s_waitcnt lgkmcnt(0)
	v_fmac_f32_e32 v37, v152, v94
	v_pk_fma_f32 v[2:3], v[154:155], v[38:39], v[2:3] op_sel_hi:[0,1,1]
	v_pk_fma_f32 v[4:5], v[154:155], v[54:55], v[4:5] op_sel_hi:[0,1,1]
	v_pk_fma_f32 v[8:9], v[154:155], v[70:71], v[8:9] op_sel_hi:[0,1,1]
	v_pk_fma_f32 v[10:11], v[154:155], v[86:87], v[10:11] op_sel_hi:[0,1,1]
	v_fmac_f32_e32 v37, v154, v95
	v_pk_fma_f32 v[2:3], v[156:157], v[6:7], v[2:3] op_sel_hi:[0,1,1]
	v_pk_fma_f32 v[4:5], v[156:157], v[46:47], v[4:5] op_sel_hi:[0,1,1]
	v_pk_fma_f32 v[6:7], v[156:157], v[62:63], v[8:9] op_sel_hi:[0,1,1]
	v_pk_fma_f32 v[8:9], v[156:157], v[78:79], v[10:11] op_sel_hi:[0,1,1]
	v_fmac_f32_e32 v37, v156, v96
	v_pk_fma_f32 v[24:25], v[158:159], v[40:41], v[2:3] op_sel_hi:[0,1,1]
	v_pk_fma_f32 v[26:27], v[158:159], v[56:57], v[4:5] op_sel_hi:[0,1,1]
	v_pk_fma_f32 v[28:29], v[158:159], v[72:73], v[6:7] op_sel_hi:[0,1,1]
	v_pk_fma_f32 v[30:31], v[158:159], v[88:89], v[8:9] op_sel_hi:[0,1,1]
	v_fmac_f32_e32 v37, v158, v97
	ds_read_b128 v[10:13], v36 offset:64
	ds_read_b128 v[6:9], v36 offset:80
	ds_read_b128 v[2:5], v36 offset:4160
	ds_read_b128 v[38:41], v36 offset:4176
	ds_read_b128 v[42:45], v36 offset:8256
	ds_read_b128 v[46:49], v36 offset:8272
	ds_read_b128 v[50:53], v36 offset:12352
	ds_read_b128 v[54:57], v36 offset:12368
	ds_read_b128 v[58:61], v36 offset:16448
	ds_read_b128 v[62:65], v36 offset:16464
	ds_read_b128 v[66:69], v36 offset:20544
	ds_read_b128 v[70:73], v36 offset:20560
	ds_read_b128 v[74:77], v36 offset:24640
	ds_read_b128 v[78:81], v36 offset:24656
	ds_read_b128 v[82:85], v36 offset:28736
	ds_read_b128 v[86:89], v36 offset:28752
	ds_read_b128 v[90:93], v36 offset:32832
	ds_read_b128 v[94:97], v36 offset:32848
	s_waitcnt vmcnt(8) lgkmcnt(1)
; DI void phase_prep(const Params& p, char* smem) {
;     ...
; #pragma unroll 8
;       for (int k = wave * 256; k < wave * 256 + 256; ++k) {
;         const float w = wa[(size_t)k * 6144];
; #pragma unroll
;         for (int b = 0; b < 9; ++b) acc[b] += sl[b * 1024 + k] * w;
;       }
	v_fmac_f32_e32 v37, v160, v90
	v_mov_b32_e32 v98, v10
	v_mov_b32_e32 v99, v2
	v_mov_b32_e32 v102, v42
	v_mov_b32_e32 v103, v50
	v_mov_b32_e32 v104, v58
	v_mov_b32_e32 v105, v66
	v_mov_b32_e32 v106, v74
	v_mov_b32_e32 v107, v82
	v_mov_b32_e32 v2, v11
	v_mov_b32_e32 v50, v43
	v_mov_b32_e32 v66, v59
	v_mov_b32_e32 v82, v75
	v_mov_b32_e32 v10, v12
	v_mov_b32_e32 v11, v4
	v_mov_b32_e32 v4, v13
	v_mov_b32_e32 v12, v6
	v_mov_b32_e32 v13, v38
	v_mov_b32_e32 v38, v7
	v_mov_b32_e32 v6, v8
	v_mov_b32_e32 v7, v40
	v_mov_b32_e32 v40, v9
	v_pk_fma_f32 v[8:9], v[160:161], v[98:99], v[24:25] op_sel_hi:[0,1,1]
	v_pk_fma_f32 v[24:25], v[160:161], v[102:103], v[26:27] op_sel_hi:[0,1,1]
	v_pk_fma_f32 v[26:27], v[160:161], v[104:105], v[28:29] op_sel_hi:[0,1,1]
	v_pk_fma_f32 v[28:29], v[160:161], v[106:107], v[30:31] op_sel_hi:[0,1,1]
	v_mov_b32_e32 v42, v44
	v_mov_b32_e32 v43, v52
	v_mov_b32_e32 v58, v60
	v_mov_b32_e32 v59, v68
	v_mov_b32_e32 v74, v76
	v_mov_b32_e32 v75, v84
	v_mov_b32_e32 v52, v45
	v_mov_b32_e32 v68, v61
	v_mov_b32_e32 v84, v77
	v_mov_b32_e32 v44, v46
	v_mov_b32_e32 v45, v54
	v_mov_b32_e32 v60, v62
	v_mov_b32_e32 v61, v70
	v_mov_b32_e32 v76, v78
	v_mov_b32_e32 v77, v86
	v_mov_b32_e32 v54, v47
	v_mov_b32_e32 v70, v63
	v_mov_b32_e32 v86, v79
	v_mov_b32_e32 v46, v48
	v_mov_b32_e32 v47, v56
	v_mov_b32_e32 v62, v64
	v_mov_b32_e32 v63, v72
	v_mov_b32_e32 v78, v80
	v_mov_b32_e32 v79, v88
	v_mov_b32_e32 v56, v49
	v_mov_b32_e32 v72, v65
	v_mov_b32_e32 v88, v81
	v_pk_fma_f32 v[2:3], v[162:163], v[2:3], v[8:9] op_sel_hi:[0,1,1]
	v_pk_fma_f32 v[8:9], v[162:163], v[50:51], v[24:25] op_sel_hi:[0,1,1]
	v_pk_fma_f32 v[24:25], v[162:163], v[66:67], v[26:27] op_sel_hi:[0,1,1]
	v_pk_fma_f32 v[26:27], v[162:163], v[82:83], v[28:29] op_sel_hi:[0,1,1]
	v_fmac_f32_e32 v37, v162, v91
	v_pk_fma_f32 v[2:3], v[164:165], v[10:11], v[2:3] op_sel_hi:[0,1,1]
	v_pk_fma_f32 v[8:9], v[164:165], v[42:43], v[8:9] op_sel_hi:[0,1,1]
	v_pk_fma_f32 v[10:11], v[164:165], v[58:59], v[24:25] op_sel_hi:[0,1,1]
	v_pk_fma_f32 v[24:25], v[164:165], v[74:75], v[26:27] op_sel_hi:[0,1,1]
	v_fmac_f32_e32 v37, v164, v92
	v_pk_fma_f32 v[2:3], v[166:167], v[4:5], v[2:3] op_sel_hi:[0,1,1]
	v_pk_fma_f32 v[4:5], v[166:167], v[52:53], v[8:9] op_sel_hi:[0,1,1]
	v_pk_fma_f32 v[8:9], v[166:167], v[68:69], v[10:11] op_sel_hi:[0,1,1]
	v_pk_fma_f32 v[10:11], v[166:167], v[84:85], v[24:25] op_sel_hi:[0,1,1]
	v_fmac_f32_e32 v37, v166, v93
	v_pk_fma_f32 v[2:3], v[168:169], v[12:13], v[2:3] op_sel_hi:[0,1,1]
	v_pk_fma_f32 v[4:5], v[168:169], v[44:45], v[4:5] op_sel_hi:[0,1,1]
	v_pk_fma_f32 v[8:9], v[168:169], v[60:61], v[8:9] op_sel_hi:[0,1,1]
	v_pk_fma_f32 v[10:11], v[168:169], v[76:77], v[10:11] op_sel_hi:[0,1,1]
	s_waitcnt lgkmcnt(0)
	v_fmac_f32_e32 v37, v168, v94
	v_pk_fma_f32 v[2:3], v[170:171], v[38:39], v[2:3] op_sel_hi:[0,1,1]
	v_pk_fma_f32 v[4:5], v[170:171], v[54:55], v[4:5] op_sel_hi:[0,1,1]
	v_pk_fma_f32 v[8:9], v[170:171], v[70:71], v[8:9] op_sel_hi:[0,1,1]
	v_pk_fma_f32 v[10:11], v[170:171], v[86:87], v[10:11] op_sel_hi:[0,1,1]
	v_fmac_f32_e32 v37, v170, v95
	v_pk_fma_f32 v[2:3], v[172:173], v[6:7], v[2:3] op_sel_hi:[0,1,1]
	v_pk_fma_f32 v[4:5], v[172:173], v[46:47], v[4:5] op_sel_hi:[0,1,1]
	v_pk_fma_f32 v[6:7], v[172:173], v[62:63], v[8:9] op_sel_hi:[0,1,1]
	v_pk_fma_f32 v[8:9], v[172:173], v[78:79], v[10:11] op_sel_hi:[0,1,1]
	v_fmac_f32_e32 v37, v172, v96
	v_pk_fma_f32 v[24:25], v[174:175], v[40:41], v[2:3] op_sel_hi:[0,1,1]
	v_pk_fma_f32 v[26:27], v[174:175], v[56:57], v[4:5] op_sel_hi:[0,1,1]
	v_pk_fma_f32 v[28:29], v[174:175], v[72:73], v[6:7] op_sel_hi:[0,1,1]
	v_pk_fma_f32 v[30:31], v[174:175], v[88:89], v[8:9] op_sel_hi:[0,1,1]
	v_fmac_f32_e32 v37, v174, v97
	ds_read_b128 v[10:13], v36 offset:96
	ds_read_b128 v[6:9], v36 offset:112
	ds_read_b128 v[2:5], v36 offset:4192
	ds_read_b128 v[38:41], v36 offset:4208
	ds_read_b128 v[42:45], v36 offset:8288
	ds_read_b128 v[46:49], v36 offset:8304
	ds_read_b128 v[50:53], v36 offset:12384
	ds_read_b128 v[54:57], v36 offset:12400
	ds_read_b128 v[58:61], v36 offset:16480
	ds_read_b128 v[62:65], v36 offset:16496
	ds_read_b128 v[66:69], v36 offset:20576
	ds_read_b128 v[70:73], v36 offset:20592
	ds_read_b128 v[74:77], v36 offset:24672
	ds_read_b128 v[78:81], v36 offset:24688
	ds_read_b128 v[82:85], v36 offset:28768
	ds_read_b128 v[86:89], v36 offset:28784
	ds_read_b128 v[90:93], v36 offset:32864
	ds_read_b128 v[94:97], v36 offset:32880
	s_waitcnt vmcnt(0) lgkmcnt(1)
; DI void phase_prep(const Params& p, char* smem) {
;     ...
; #pragma unroll 8
;       for (int k = wave * 256; k < wave * 256 + 256; ++k) {
;         const float w = wa[(size_t)k * 6144];
; #pragma unroll
;         for (int b = 0; b < 9; ++b) acc[b] += sl[b * 1024 + k] * w;
;       }
; #pragma unroll
;       for (int b = 0; b < 9; ++b) red[(wave * 9 + b) * 64 + lane] = acc[b];
;       __syncthreads();
;       for (int e = tid; e < 9 * 64; e += 256) {
;         const int b = e >> 6, c = e & 63;
;         const float s = red[(0 * 9 + b) * 64 + c] + red[(1 * 9 + b) * 64 + c] + red[(2 * 9 + b) * 64 + c] + red[(3 * 9 + b) * 64 + c];
;         ((float*)(p.ws + OFF_MODS))[(size_t)(l * 9 + b) * 6144 + cg_ * 64 + c] = s + p.in[I_BADA][l * 6144 + cg_ * 64 + c];
	v_fmac_f32_e32 v37, v176, v90
	v_mov_b32_e32 v98, v10
	v_mov_b32_e32 v99, v2
	v_mov_b32_e32 v102, v42
	v_mov_b32_e32 v103, v50
	v_mov_b32_e32 v104, v58
	v_mov_b32_e32 v105, v66
	v_mov_b32_e32 v106, v74
	v_mov_b32_e32 v107, v82
	v_mov_b32_e32 v2, v11
	v_mov_b32_e32 v50, v43
	v_mov_b32_e32 v66, v59
	v_mov_b32_e32 v82, v75
	v_mov_b32_e32 v10, v12
	v_mov_b32_e32 v11, v4
	v_mov_b32_e32 v4, v13
	v_mov_b32_e32 v12, v6
	v_mov_b32_e32 v13, v38
	v_mov_b32_e32 v38, v7
	v_mov_b32_e32 v6, v8
	v_mov_b32_e32 v7, v40
	v_mov_b32_e32 v40, v9
	v_pk_fma_f32 v[8:9], v[176:177], v[98:99], v[24:25] op_sel_hi:[0,1,1]
	v_pk_fma_f32 v[24:25], v[176:177], v[102:103], v[26:27] op_sel_hi:[0,1,1]
	v_pk_fma_f32 v[26:27], v[176:177], v[104:105], v[28:29] op_sel_hi:[0,1,1]
	v_pk_fma_f32 v[28:29], v[176:177], v[106:107], v[30:31] op_sel_hi:[0,1,1]
	v_mov_b32_e32 v42, v44
	v_mov_b32_e32 v43, v52
	v_mov_b32_e32 v58, v60
	v_mov_b32_e32 v59, v68
	v_mov_b32_e32 v74, v76
	v_mov_b32_e32 v75, v84
	v_mov_b32_e32 v52, v45
	v_mov_b32_e32 v68, v61
	v_mov_b32_e32 v84, v77
	v_mov_b32_e32 v44, v46
	v_mov_b32_e32 v45, v54
	v_mov_b32_e32 v60, v62
	v_mov_b32_e32 v61, v70
	v_mov_b32_e32 v76, v78
	v_mov_b32_e32 v77, v86
	v_mov_b32_e32 v54, v47
	v_mov_b32_e32 v70, v63
	v_mov_b32_e32 v86, v79
	v_mov_b32_e32 v46, v48
	v_mov_b32_e32 v47, v56
	v_mov_b32_e32 v62, v64
	v_mov_b32_e32 v63, v72
	v_mov_b32_e32 v78, v80
	v_mov_b32_e32 v79, v88
	v_mov_b32_e32 v56, v49
	v_mov_b32_e32 v72, v65
	v_mov_b32_e32 v88, v81
	v_pk_fma_f32 v[2:3], v[178:179], v[2:3], v[8:9] op_sel_hi:[0,1,1]
	v_pk_fma_f32 v[8:9], v[178:179], v[50:51], v[24:25] op_sel_hi:[0,1,1]
	v_pk_fma_f32 v[24:25], v[178:179], v[66:67], v[26:27] op_sel_hi:[0,1,1]
	v_pk_fma_f32 v[26:27], v[178:179], v[82:83], v[28:29] op_sel_hi:[0,1,1]
	v_fmac_f32_e32 v37, v178, v91
	v_pk_fma_f32 v[2:3], v[180:181], v[10:11], v[2:3] op_sel_hi:[0,1,1]
	v_pk_fma_f32 v[8:9], v[180:181], v[42:43], v[8:9] op_sel_hi:[0,1,1]
	v_pk_fma_f32 v[10:11], v[180:181], v[58:59], v[24:25] op_sel_hi:[0,1,1]
	v_pk_fma_f32 v[24:25], v[180:181], v[74:75], v[26:27] op_sel_hi:[0,1,1]
	v_fmac_f32_e32 v37, v180, v92
	v_pk_fma_f32 v[2:3], v[182:183], v[4:5], v[2:3] op_sel_hi:[0,1,1]
	v_pk_fma_f32 v[4:5], v[182:183], v[52:53], v[8:9] op_sel_hi:[0,1,1]
	v_pk_fma_f32 v[8:9], v[182:183], v[68:69], v[10:11] op_sel_hi:[0,1,1]
	v_pk_fma_f32 v[10:11], v[182:183], v[84:85], v[24:25] op_sel_hi:[0,1,1]
	v_fmac_f32_e32 v37, v182, v93
	v_pk_fma_f32 v[2:3], v[184:185], v[12:13], v[2:3] op_sel_hi:[0,1,1]
	v_pk_fma_f32 v[4:5], v[184:185], v[44:45], v[4:5] op_sel_hi:[0,1,1]
	v_pk_fma_f32 v[8:9], v[184:185], v[60:61], v[8:9] op_sel_hi:[0,1,1]
	v_pk_fma_f32 v[10:11], v[184:185], v[76:77], v[10:11] op_sel_hi:[0,1,1]
	s_waitcnt lgkmcnt(0)
	v_fmac_f32_e32 v37, v184, v94
	v_pk_fma_f32 v[2:3], v[186:187], v[38:39], v[2:3] op_sel_hi:[0,1,1]
	v_pk_fma_f32 v[4:5], v[186:187], v[54:55], v[4:5] op_sel_hi:[0,1,1]
	v_pk_fma_f32 v[8:9], v[186:187], v[70:71], v[8:9] op_sel_hi:[0,1,1]
	v_pk_fma_f32 v[10:11], v[186:187], v[86:87], v[10:11] op_sel_hi:[0,1,1]
	v_fmac_f32_e32 v37, v186, v95
	v_pk_fma_f32 v[2:3], v[188:189], v[6:7], v[2:3] op_sel_hi:[0,1,1]
	v_pk_fma_f32 v[4:5], v[188:189], v[46:47], v[4:5] op_sel_hi:[0,1,1]
	v_pk_fma_f32 v[6:7], v[188:189], v[62:63], v[8:9] op_sel_hi:[0,1,1]
	v_pk_fma_f32 v[8:9], v[188:189], v[78:79], v[10:11] op_sel_hi:[0,1,1]
	v_fmac_f32_e32 v37, v188, v96
	v_pk_fma_f32 v[24:25], v[190:191], v[40:41], v[2:3] op_sel_hi:[0,1,1]
	v_pk_fma_f32 v[26:27], v[190:191], v[56:57], v[4:5] op_sel_hi:[0,1,1]
	v_pk_fma_f32 v[28:29], v[190:191], v[72:73], v[6:7] op_sel_hi:[0,1,1]
	v_pk_fma_f32 v[30:31], v[190:191], v[88:89], v[8:9] op_sel_hi:[0,1,1]
	v_fmac_f32_e32 v37, v190, v97
	v_add_u32_e32 v36, 0x80, v36
	s_cmp_eq_u32 s8, 0x600000
	s_cbranch_scc0 .LBB0_320
	ds_write2st64_b32 v35, v24, v25 offset0:144 offset1:145
	ds_write2st64_b32 v35, v26, v27 offset0:146 offset1:147
	ds_write2st64_b32 v35, v28, v29 offset0:148 offset1:149
	ds_write2st64_b32 v35, v30, v31 offset0:150 offset1:151
	ds_write_b32 v35, v37 offset:38912
	s_waitcnt lgkmcnt(0)
	s_barrier
	s_and_saveexec_b64 s[8:9], vcc
	s_cbranch_execz .LBB0_318
	s_mul_i32 s4, s10, 0xffffffa0
	s_add_i32 s4, s4, s3
	s_lshl_b32 s4, s4, 6
	s_add_i32 s11, s4, s11
	v_or_b32_e32 v2, s11, v1
	s_ashr_i32 s5, s4, 31
	v_ashrrev_i32_e32 v3, 31, v2
	s_mul_i32 s22, s10, 9
	v_lshl_add_u64 v[2:3], v[2:3], 2, s[6:7]
	v_lshl_add_u64 v[4:5], s[4:5], 2, v[18:19]
	s_mov_b64 s[10:11], 0
	v_mov_b32_e32 v6, v33
	v_mov_b32_e32 v7, v14
